# SEL loop: K/V blocks staged by LDS-DMA (global_load_lds_dwordx4) into a double-buffered LDS image, loop unrolled x2, one barrier per block
# speedup vs baseline: 1.1488x; 1.0356x over previous
.LBB0_1618:
	s_lshl_b64 s[0:1], s[66:67], 22
	s_add_u32 s18, s90, s0
	s_addc_u32 s19, s91, s1
	s_add_u32 s20, s92, s0
	v_cndmask_b32_e64 v0, 0, 1, s[22:23]
	s_addc_u32 s21, s93, s1
	v_cmp_ne_u32_e64 s[0:1], 1, v0
	v_lshlrev_b32_e32 v0, 5, v3
	s_andn2_b64 vcc, exec, s[22:23]
	v_ashrrev_i32_e32 v1, 31, v0
	s_cbranch_vccnz .LBB0_1620
	v_add_u32_e32 v116, 0x1000, v250
	v_add_u32_e32 v117, 0x2000, v249
	v_add_u32_e32 v118, 0x3000, v250
	v_add_u32_e32 v119, 0x1000, v251
	v_add_u32_e32 v120, 0x2000, v251
	v_add_u32_e32 v121, 0x3000, v251
	v_lshrrev_b32_e32 v122, 6, v220
	v_lshlrev_b32_e32 v122, 10, v122
	v_mov_b32_e32 v143, 0
	v_mov_b32_e32 v142, v249
	v_lshl_add_u64 v[124:125], s[18:19], 0, v[142:143]
	v_mov_b32_e32 v142, v116
	v_lshl_add_u64 v[126:127], s[18:19], 0, v[142:143]
	v_mov_b32_e32 v142, v117
	v_lshl_add_u64 v[128:129], s[18:19], 0, v[142:143]
	v_mov_b32_e32 v142, v118
	v_lshl_add_u64 v[130:131], s[18:19], 0, v[142:143]
	v_mov_b32_e32 v142, v251
	v_lshl_add_u64 v[132:133], s[20:21], 0, v[142:143]
	v_mov_b32_e32 v142, v119
	v_lshl_add_u64 v[134:135], s[20:21], 0, v[142:143]
	v_mov_b32_e32 v142, v120
	v_lshl_add_u64 v[136:137], s[20:21], 0, v[142:143]
	v_mov_b32_e32 v142, v121
	v_lshl_add_u64 v[138:139], s[20:21], 0, v[142:143]
	s_lshl_b32 s24, s94, 14
	s_mov_b32 s25, 0
	v_readfirstlane_b32 vcc_lo, v122
	s_mov_b32 m0, vcc_lo
	v_lshl_add_u64 v[140:141], v[124:125], 0, s[24:25]
	global_load_lds_dwordx4 v[140:141], off
	s_add_u32 m0, m0, 0x1000
	v_lshl_add_u64 v[140:141], v[126:127], 0, s[24:25]
	global_load_lds_dwordx4 v[140:141], off
	s_add_u32 m0, m0, 0x1000
	v_lshl_add_u64 v[140:141], v[128:129], 0, s[24:25]
	global_load_lds_dwordx4 v[140:141], off
	s_add_u32 m0, m0, 0x1000
	v_lshl_add_u64 v[140:141], v[130:131], 0, s[24:25]
	global_load_lds_dwordx4 v[140:141], off
	s_add_u32 m0, m0, 0x1000
	v_lshl_add_u64 v[140:141], v[132:133], 0, s[24:25]
	global_load_lds_dwordx4 v[140:141], off
	s_add_u32 m0, m0, 0x1000
	v_lshl_add_u64 v[140:141], v[134:135], 0, s[24:25]
	global_load_lds_dwordx4 v[140:141], off
	s_add_u32 m0, m0, 0x1000
	v_lshl_add_u64 v[140:141], v[136:137], 0, s[24:25]
	global_load_lds_dwordx4 v[140:141], off
	s_add_u32 m0, m0, 0x1000
	v_lshl_add_u64 v[140:141], v[138:139], 0, s[24:25]
	global_load_lds_dwordx4 v[140:141], off

.LBB0_1622:
	s_cmpk_gt_u32 s94, 0xfe
	s_movk_i32 s95, 0x100
	s_cbranch_scc1 .LBB0_1632
	s_add_i32 s22, s94, 1
	s_cmp_gt_u32 s94, 62
	s_cselect_b64 s[18:19], -1, 0
	s_lshl_b64 s[0:1], -1, s22
	s_and_b64 s[20:21], s[0:1], s[10:11]
	s_cmp_eq_u64 s[20:21], 0
	s_cselect_b64 s[24:25], -1, 0
	s_or_b64 s[24:25], s[18:19], s[24:25]
	s_mov_b64 s[18:19], -1
	s_and_b64 vcc, exec, s[24:25]
	s_cbranch_vccnz .LBB0_1625
	s_ff1_i32_b64 s95, s[20:21]
	s_mov_b64 s[18:19], 0

.LBB0_1632:
	s_waitcnt vmcnt(0) lgkmcnt(0)
	s_barrier
	s_min_u32 s0, s95, 0xff
	s_lshl_b32 s0, s0, 2
	s_add_i32 s18, s0, 0x10200
	s_cmp_gt_u32 s95, s86
	s_cselect_b64 s[78:79], -1, 0
	s_and_b64 s[0:1], s[78:79], exec
	s_cselect_b32 s0, s94, s95
	s_lshl_b32 s56, s0, 14
	v_readfirstlane_b32 s24, v122
	s_add_i32 m0, s24, 0x8000
	v_lshl_add_u64 v[140:141], v[124:125], 0, s[56:57]
	global_load_lds_dwordx4 v[140:141], off
	s_add_u32 m0, m0, 0x1000
	v_lshl_add_u64 v[140:141], v[126:127], 0, s[56:57]
	global_load_lds_dwordx4 v[140:141], off
	s_add_u32 m0, m0, 0x1000
	v_lshl_add_u64 v[140:141], v[128:129], 0, s[56:57]
	global_load_lds_dwordx4 v[140:141], off
	s_add_u32 m0, m0, 0x1000
	v_lshl_add_u64 v[140:141], v[130:131], 0, s[56:57]
	global_load_lds_dwordx4 v[140:141], off
	s_add_u32 m0, m0, 0x1000
	v_lshl_add_u64 v[140:141], v[132:133], 0, s[56:57]
	global_load_lds_dwordx4 v[140:141], off
	s_add_u32 m0, m0, 0x1000
	v_lshl_add_u64 v[140:141], v[134:135], 0, s[56:57]
	global_load_lds_dwordx4 v[140:141], off
	s_add_u32 m0, m0, 0x1000
	v_lshl_add_u64 v[140:141], v[136:137], 0, s[56:57]
	global_load_lds_dwordx4 v[140:141], off
	s_add_u32 m0, m0, 0x1000
	v_lshl_add_u64 v[140:141], v[138:139], 0, s[56:57]
	global_load_lds_dwordx4 v[140:141], off
	v_mov_b32_e32 v0, s18
	ds_read_b32 v19, v0
	v_readfirstlane_b32 s0, v2
	s_nop 1
	v_ashrrev_i32_e64 v207, v185, s0
	v_and_b32_e32 v0, 15, v207
	v_cmp_ne_u32_e32 vcc, 0, v0
	s_and_saveexec_b64 s[80:81], vcc
	s_cbranch_execz .LBB0_1642
	ds_read_b128 v[0:3], v187
	ds_read_b128 v[4:7], v188
	ds_read_b128 v[8:11], v189
	ds_read_b128 v[12:15], v190
	ds_read_b128 v[148:151], v191
	ds_read_b128 v[152:155], v192
	ds_read_b128 v[156:159], v193
	ds_read_b128 v[208:211], v194
	s_waitcnt lgkmcnt(7)
	v_mfma_f32_16x16x32_bf16 v[0:3], v[0:3], v[20:23], 0
	s_waitcnt lgkmcnt(6)
	v_mfma_f32_16x16x32_bf16 v[4:7], v[4:7], v[20:23], 0
	s_waitcnt lgkmcnt(5)
	v_mfma_f32_16x16x32_bf16 v[0:3], v[8:11], v[24:27], v[0:3]
	s_waitcnt lgkmcnt(4)
	v_mfma_f32_16x16x32_bf16 v[4:7], v[12:15], v[24:27], v[4:7]
	s_waitcnt lgkmcnt(3)
	v_mfma_f32_16x16x32_bf16 v[0:3], v[148:151], v[28:31], v[0:3]
	s_waitcnt lgkmcnt(2)
	v_mfma_f32_16x16x32_bf16 v[4:7], v[152:155], v[28:31], v[4:7]
	s_waitcnt lgkmcnt(1)
	v_mfma_f32_16x16x32_bf16 v[160:163], v[156:159], v[32:35], v[0:3]
	s_waitcnt lgkmcnt(0)
	v_mfma_f32_16x16x32_bf16 v[156:159], v[208:211], v[32:35], v[4:7]
	s_nop 1
	v_and_b32_e32 v0, v207, v186
	v_cmp_ne_u32_e64 s[82:83], 0, v0
	ds_read_b128 v[0:3], v187 offset:8192
	ds_read_b128 v[4:7], v195
	ds_read_b128 v[8:11], v189 offset:8192
	ds_read_b128 v[12:15], v196
	ds_read_b128 v[148:151], v191 offset:8192
	ds_read_b128 v[152:155], v197
	ds_read_b128 v[208:211], v193 offset:8192
	ds_read_b128 v[212:215], v198
	s_waitcnt lgkmcnt(7)
	v_mfma_f32_16x16x32_bf16 v[0:3], v[0:3], v[20:23], 0
	s_waitcnt lgkmcnt(6)
	v_mfma_f32_16x16x32_bf16 v[4:7], v[4:7], v[20:23], 0
	s_waitcnt lgkmcnt(5)
	v_mfma_f32_16x16x32_bf16 v[0:3], v[8:11], v[24:27], v[0:3]
	s_waitcnt lgkmcnt(4)
	v_mfma_f32_16x16x32_bf16 v[4:7], v[12:15], v[24:27], v[4:7]
	s_waitcnt lgkmcnt(3)
	v_mfma_f32_16x16x32_bf16 v[0:3], v[148:151], v[28:31], v[0:3]
	s_waitcnt lgkmcnt(2)
	v_mfma_f32_16x16x32_bf16 v[4:7], v[152:155], v[28:31], v[4:7]
	s_waitcnt lgkmcnt(1)
	v_mfma_f32_16x16x32_bf16 v[152:155], v[208:211], v[32:35], v[0:3]
	s_waitcnt lgkmcnt(0)
	v_mfma_f32_16x16x32_bf16 v[148:151], v[212:215], v[32:35], v[4:7]
	s_lshl_b32 s33, s94, 6
	s_or_b32 s0, s33, 63
	v_cmp_le_i32_e32 vcc, s0, v199
	s_and_saveexec_b64 s[0:1], vcc
	s_xor_b64 s[0:1], exec, s[0:1]
	s_or_saveexec_b64 s[26:27], s[0:1]
	s_mov_b64 s[84:85], s[82:83]
	s_xor_b64 exec, exec, s[26:27]
	s_cbranch_execz .LBB0_1635
	v_cndmask_b32_e64 v1, 0, -1, s[82:83]
	v_or_b32_e32 v2, s33, v201
	v_cndmask_b32_e64 v0, -1, v200, s[82:83]
	v_cmp_gt_i32_e64 s[0:1], v2, v1
	v_or_b32_e32 v1, 2, v2
	v_cmp_le_i32_e64 s[20:21], v1, v0
	v_or_b32_e32 v1, 3, v2
	v_cmp_le_i32_e64 s[22:23], v1, v0
	v_or_b32_e32 v1, 4, v2
	v_cmp_le_i32_e64 s[24:25], v1, v0
	v_or_b32_e32 v1, 5, v2
	v_cmp_le_i32_e64 s[28:29], v1, v0
	v_or_b32_e32 v1, 6, v2
	v_cmp_le_i32_e64 s[30:31], v1, v0
	v_or_b32_e32 v1, 7, v2
	v_cmp_le_i32_e64 s[34:35], v1, v0
	v_or_b32_e32 v1, 32, v2
	v_cmp_le_i32_e64 s[36:37], v1, v0
	v_cmp_lt_i32_e64 s[38:39], v1, v0
	v_or_b32_e32 v1, 34, v2
	v_cmp_le_i32_e64 s[40:41], v1, v0
	v_or_b32_e32 v1, 35, v2
	v_cmp_le_i32_e64 s[42:43], v1, v0
	v_or_b32_e32 v1, 36, v2
	v_cmp_le_i32_e64 s[44:45], v1, v0
	v_or_b32_e32 v1, 37, v2
	v_cmp_le_i32_e64 s[46:47], v1, v0
	v_or_b32_e32 v1, 38, v2
	v_cmp_le_i32_e64 s[18:19], v2, v0
	v_cmp_le_i32_e64 s[48:49], v1, v0
	v_or_b32_e32 v1, 39, v2
	s_and_b64 s[0:1], s[0:1], s[18:19]
	v_cmp_lt_i32_e64 s[18:19], v2, v0
	v_cmp_le_i32_e64 s[50:51], v1, v0
	v_cndmask_b32_e64 v160, v169, v160, s[0:1]
	v_cndmask_b32_e64 v161, v169, v161, s[18:19]
	v_cndmask_b32_e64 v162, v169, v162, s[20:21]
	v_cndmask_b32_e64 v163, v169, v163, s[22:23]
	v_cndmask_b32_e64 v156, v169, v156, s[24:25]
	v_cndmask_b32_e64 v157, v169, v157, s[28:29]
	v_cndmask_b32_e64 v158, v169, v158, s[30:31]
	v_cndmask_b32_e64 v159, v169, v159, s[34:35]
	v_cndmask_b32_e64 v152, v169, v152, s[36:37]
	v_cndmask_b32_e64 v153, v169, v153, s[38:39]
	v_cndmask_b32_e64 v154, v169, v154, s[40:41]
	v_cndmask_b32_e64 v155, v169, v155, s[42:43]
	v_cndmask_b32_e64 v148, v169, v148, s[44:45]
	v_cndmask_b32_e64 v149, v169, v149, s[46:47]
	v_cndmask_b32_e64 v150, v169, v150, s[48:49]
	v_cndmask_b32_e64 v151, v169, v151, s[50:51]
	s_andn2_b64 s[54:55], s[82:83], exec
	s_and_b64 s[50:51], s[50:51], exec
	s_and_b64 s[48:49], s[48:49], exec
	s_and_b64 s[46:47], s[46:47], exec
	s_and_b64 s[44:45], s[44:45], exec
	s_and_b64 s[42:43], s[42:43], exec
	s_and_b64 s[40:41], s[40:41], exec
	s_and_b64 s[38:39], s[38:39], exec
	s_and_b64 s[36:37], s[36:37], exec
	s_and_b64 s[34:35], s[34:35], exec
	s_and_b64 s[30:31], s[30:31], exec
	s_and_b64 s[28:29], s[28:29], exec
	s_and_b64 s[24:25], s[24:25], exec
	s_and_b64 s[22:23], s[22:23], exec
	s_and_b64 s[20:21], s[20:21], exec
	s_and_b64 s[18:19], s[18:19], exec
	s_and_b64 s[0:1], s[0:1], exec
	s_or_b64 s[84:85], s[82:83], exec
	s_or_b64 s[50:51], s[54:55], s[50:51]
	s_or_b64 s[48:49], s[54:55], s[48:49]
	s_or_b64 s[46:47], s[54:55], s[46:47]
	s_or_b64 s[44:45], s[54:55], s[44:45]
	s_or_b64 s[42:43], s[54:55], s[42:43]
	s_or_b64 s[40:41], s[54:55], s[40:41]
	s_or_b64 s[38:39], s[54:55], s[38:39]
	s_or_b64 s[36:37], s[54:55], s[36:37]
	s_or_b64 s[34:35], s[54:55], s[34:35]
	s_or_b64 s[30:31], s[54:55], s[30:31]
	s_or_b64 s[28:29], s[54:55], s[28:29]
	s_or_b64 s[24:25], s[54:55], s[24:25]
	s_or_b64 s[22:23], s[54:55], s[22:23]
	s_or_b64 s[20:21], s[54:55], s[20:21]
	s_or_b64 s[18:19], s[54:55], s[18:19]
	s_or_b64 s[0:1], s[54:55], s[0:1]

.LBB0_1652:
	s_or_b64 exec, exec, s[80:81]
	s_andn2_b64 vcc, exec, s[78:79]
	s_cbranch_vccz .Lsel_exit
	s_waitcnt lgkmcnt(0)
	v_mov_b32_e32 v2, v19
	s_mov_b32 s94, s95
	s_branch .Lselb_1622

.Lselb_1632:
	s_waitcnt vmcnt(0) lgkmcnt(0)
	s_barrier
	s_min_u32 s0, s95, 0xff
	s_lshl_b32 s0, s0, 2
	s_add_i32 s18, s0, 0x10200
	s_cmp_gt_u32 s95, s86
	s_cselect_b64 s[78:79], -1, 0
	s_and_b64 s[0:1], s[78:79], exec
	s_cselect_b32 s0, s94, s95
	s_lshl_b32 s56, s0, 14
	v_readfirstlane_b32 s24, v122
	s_mov_b32 m0, s24
	v_lshl_add_u64 v[140:141], v[124:125], 0, s[56:57]
	global_load_lds_dwordx4 v[140:141], off
	s_add_u32 m0, m0, 0x1000
	v_lshl_add_u64 v[140:141], v[126:127], 0, s[56:57]
	global_load_lds_dwordx4 v[140:141], off
	s_add_u32 m0, m0, 0x1000
	v_lshl_add_u64 v[140:141], v[128:129], 0, s[56:57]
	global_load_lds_dwordx4 v[140:141], off
	s_add_u32 m0, m0, 0x1000
	v_lshl_add_u64 v[140:141], v[130:131], 0, s[56:57]
	global_load_lds_dwordx4 v[140:141], off
	s_add_u32 m0, m0, 0x1000
	v_lshl_add_u64 v[140:141], v[132:133], 0, s[56:57]
	global_load_lds_dwordx4 v[140:141], off
	s_add_u32 m0, m0, 0x1000
	v_lshl_add_u64 v[140:141], v[134:135], 0, s[56:57]
	global_load_lds_dwordx4 v[140:141], off
	s_add_u32 m0, m0, 0x1000
	v_lshl_add_u64 v[140:141], v[136:137], 0, s[56:57]
	global_load_lds_dwordx4 v[140:141], off
	s_add_u32 m0, m0, 0x1000
	v_lshl_add_u64 v[140:141], v[138:139], 0, s[56:57]
	global_load_lds_dwordx4 v[140:141], off
	v_mov_b32_e32 v0, s18
	ds_read_b32 v19, v0
	v_readfirstlane_b32 s0, v2
	s_nop 1
	v_ashrrev_i32_e64 v207, v185, s0
	v_and_b32_e32 v0, 15, v207
	v_cmp_ne_u32_e32 vcc, 0, v0
	s_and_saveexec_b64 s[80:81], vcc
	s_cbranch_execz .Lselb_1642
	ds_read_b128 v[0:3], v187 offset:32768
	ds_read_b128 v[4:7], v188 offset:32768
	ds_read_b128 v[8:11], v189 offset:32768
	ds_read_b128 v[12:15], v190 offset:32768
	ds_read_b128 v[148:151], v191 offset:32768
	ds_read_b128 v[152:155], v192 offset:32768
	ds_read_b128 v[156:159], v193 offset:32768
	ds_read_b128 v[208:211], v194 offset:32768
	s_waitcnt lgkmcnt(7)
	v_mfma_f32_16x16x32_bf16 v[0:3], v[0:3], v[20:23], 0
	s_waitcnt lgkmcnt(6)
	v_mfma_f32_16x16x32_bf16 v[4:7], v[4:7], v[20:23], 0
	s_waitcnt lgkmcnt(5)
	v_mfma_f32_16x16x32_bf16 v[0:3], v[8:11], v[24:27], v[0:3]
	s_waitcnt lgkmcnt(4)
	v_mfma_f32_16x16x32_bf16 v[4:7], v[12:15], v[24:27], v[4:7]
	s_waitcnt lgkmcnt(3)
	v_mfma_f32_16x16x32_bf16 v[0:3], v[148:151], v[28:31], v[0:3]
	s_waitcnt lgkmcnt(2)
	v_mfma_f32_16x16x32_bf16 v[4:7], v[152:155], v[28:31], v[4:7]
	s_waitcnt lgkmcnt(1)
	v_mfma_f32_16x16x32_bf16 v[160:163], v[156:159], v[32:35], v[0:3]
	s_waitcnt lgkmcnt(0)
	v_mfma_f32_16x16x32_bf16 v[156:159], v[208:211], v[32:35], v[4:7]
	s_nop 1
	v_and_b32_e32 v0, v207, v186
	v_cmp_ne_u32_e64 s[82:83], 0, v0
	ds_read_b128 v[0:3], v187 offset:40960
	ds_read_b128 v[4:7], v195 offset:32768
	ds_read_b128 v[8:11], v189 offset:40960
	ds_read_b128 v[12:15], v196 offset:32768
	ds_read_b128 v[148:151], v191 offset:40960
	ds_read_b128 v[152:155], v197 offset:32768
	ds_read_b128 v[208:211], v193 offset:40960
	ds_read_b128 v[212:215], v198 offset:32768
	s_waitcnt lgkmcnt(7)
	v_mfma_f32_16x16x32_bf16 v[0:3], v[0:3], v[20:23], 0
	s_waitcnt lgkmcnt(6)
	v_mfma_f32_16x16x32_bf16 v[4:7], v[4:7], v[20:23], 0
	s_waitcnt lgkmcnt(5)
	v_mfma_f32_16x16x32_bf16 v[0:3], v[8:11], v[24:27], v[0:3]
	s_waitcnt lgkmcnt(4)
	v_mfma_f32_16x16x32_bf16 v[4:7], v[12:15], v[24:27], v[4:7]
	s_waitcnt lgkmcnt(3)
	v_mfma_f32_16x16x32_bf16 v[0:3], v[148:151], v[28:31], v[0:3]
	s_waitcnt lgkmcnt(2)
	v_mfma_f32_16x16x32_bf16 v[4:7], v[152:155], v[28:31], v[4:7]
	s_waitcnt lgkmcnt(1)
	v_mfma_f32_16x16x32_bf16 v[152:155], v[208:211], v[32:35], v[0:3]
	s_waitcnt lgkmcnt(0)
	v_mfma_f32_16x16x32_bf16 v[148:151], v[212:215], v[32:35], v[4:7]
	s_lshl_b32 s33, s94, 6
	s_or_b32 s0, s33, 63
	v_cmp_le_i32_e32 vcc, s0, v199
	s_and_saveexec_b64 s[0:1], vcc
	s_xor_b64 s[0:1], exec, s[0:1]
	s_or_saveexec_b64 s[26:27], s[0:1]
	s_mov_b64 s[84:85], s[82:83]
	s_xor_b64 exec, exec, s[26:27]
	s_cbranch_execz .Lselb_1635
	v_cndmask_b32_e64 v1, 0, -1, s[82:83]
	v_or_b32_e32 v2, s33, v201
	v_cndmask_b32_e64 v0, -1, v200, s[82:83]
	v_cmp_gt_i32_e64 s[0:1], v2, v1
	v_or_b32_e32 v1, 2, v2
	v_cmp_le_i32_e64 s[20:21], v1, v0
	v_or_b32_e32 v1, 3, v2
	v_cmp_le_i32_e64 s[22:23], v1, v0
	v_or_b32_e32 v1, 4, v2
	v_cmp_le_i32_e64 s[24:25], v1, v0
	v_or_b32_e32 v1, 5, v2
	v_cmp_le_i32_e64 s[28:29], v1, v0
	v_or_b32_e32 v1, 6, v2
	v_cmp_le_i32_e64 s[30:31], v1, v0
	v_or_b32_e32 v1, 7, v2
	v_cmp_le_i32_e64 s[34:35], v1, v0
	v_or_b32_e32 v1, 32, v2
	v_cmp_le_i32_e64 s[36:37], v1, v0
	v_cmp_lt_i32_e64 s[38:39], v1, v0
	v_or_b32_e32 v1, 34, v2
	v_cmp_le_i32_e64 s[40:41], v1, v0
	v_or_b32_e32 v1, 35, v2
	v_cmp_le_i32_e64 s[42:43], v1, v0
	v_or_b32_e32 v1, 36, v2
	v_cmp_le_i32_e64 s[44:45], v1, v0
	v_or_b32_e32 v1, 37, v2
	v_cmp_le_i32_e64 s[46:47], v1, v0
	v_or_b32_e32 v1, 38, v2
	v_cmp_le_i32_e64 s[18:19], v2, v0
	v_cmp_le_i32_e64 s[48:49], v1, v0
	v_or_b32_e32 v1, 39, v2
	s_and_b64 s[0:1], s[0:1], s[18:19]
	v_cmp_lt_i32_e64 s[18:19], v2, v0
	v_cmp_le_i32_e64 s[50:51], v1, v0
	v_cndmask_b32_e64 v160, v169, v160, s[0:1]
	v_cndmask_b32_e64 v161, v169, v161, s[18:19]
	v_cndmask_b32_e64 v162, v169, v162, s[20:21]
	v_cndmask_b32_e64 v163, v169, v163, s[22:23]
	v_cndmask_b32_e64 v156, v169, v156, s[24:25]
	v_cndmask_b32_e64 v157, v169, v157, s[28:29]
	v_cndmask_b32_e64 v158, v169, v158, s[30:31]
	v_cndmask_b32_e64 v159, v169, v159, s[34:35]
	v_cndmask_b32_e64 v152, v169, v152, s[36:37]
	v_cndmask_b32_e64 v153, v169, v153, s[38:39]
	v_cndmask_b32_e64 v154, v169, v154, s[40:41]
	v_cndmask_b32_e64 v155, v169, v155, s[42:43]
	v_cndmask_b32_e64 v148, v169, v148, s[44:45]
	v_cndmask_b32_e64 v149, v169, v149, s[46:47]
	v_cndmask_b32_e64 v150, v169, v150, s[48:49]
	v_cndmask_b32_e64 v151, v169, v151, s[50:51]
	s_andn2_b64 s[54:55], s[82:83], exec
	s_and_b64 s[50:51], s[50:51], exec
	s_and_b64 s[48:49], s[48:49], exec
	s_and_b64 s[46:47], s[46:47], exec
	s_and_b64 s[44:45], s[44:45], exec
	s_and_b64 s[42:43], s[42:43], exec
	s_and_b64 s[40:41], s[40:41], exec
	s_and_b64 s[38:39], s[38:39], exec
	s_and_b64 s[36:37], s[36:37], exec
	s_and_b64 s[34:35], s[34:35], exec
	s_and_b64 s[30:31], s[30:31], exec
	s_and_b64 s[28:29], s[28:29], exec
	s_and_b64 s[24:25], s[24:25], exec
	s_and_b64 s[22:23], s[22:23], exec
	s_and_b64 s[20:21], s[20:21], exec
	s_and_b64 s[18:19], s[18:19], exec
	s_and_b64 s[0:1], s[0:1], exec
	s_or_b64 s[84:85], s[82:83], exec
	s_or_b64 s[50:51], s[54:55], s[50:51]
	s_or_b64 s[48:49], s[54:55], s[48:49]
	s_or_b64 s[46:47], s[54:55], s[46:47]
	s_or_b64 s[44:45], s[54:55], s[44:45]
	s_or_b64 s[42:43], s[54:55], s[42:43]
	s_or_b64 s[40:41], s[54:55], s[40:41]
	s_or_b64 s[38:39], s[54:55], s[38:39]
	s_or_b64 s[36:37], s[54:55], s[36:37]
	s_or_b64 s[34:35], s[54:55], s[34:35]
	s_or_b64 s[30:31], s[54:55], s[30:31]
	s_or_b64 s[28:29], s[54:55], s[28:29]
	s_or_b64 s[24:25], s[54:55], s[24:25]
	s_or_b64 s[22:23], s[54:55], s[22:23]
	s_or_b64 s[20:21], s[54:55], s[20:21]
	s_or_b64 s[18:19], s[54:55], s[18:19]
	s_or_b64 s[0:1], s[54:55], s[0:1]

.Lselb_1641:
	v_fmac_f32_e32 v209, v176, v16
	v_add_u32_e32 v16, v202, v203
	v_cvt_pk_bf16_f32 v148, v0, v1
	v_cvt_pk_bf16_f32 v149, v2, v3
	v_cvt_pk_bf16_f32 v150, v4, v5
	v_cvt_pk_bf16_f32 v151, v6, v7
	s_nop 1
	ds_read_b128 v[152:155], v16 offset:53248
	ds_read_b128 v[156:159], v16 offset:55296
	ds_read_b128 v[160:163], v16 offset:57344
	ds_read_b128 v[210:213], v16 offset:59392
	ds_read_b128 v[214:217], v16 offset:61440
	ds_read_b128 v[222:225], v16 offset:63488
	ds_read_b128 v[0:3], v16 offset:49152
	ds_read_b128 v[4:7], v16 offset:51200
	s_waitcnt lgkmcnt(7)
	v_mfma_f32_16x16x32_bf16 v[104:107], v[152:155], v[148:151], v[104:107]
	s_waitcnt lgkmcnt(6)
	v_mfma_f32_16x16x32_bf16 v[100:103], v[156:159], v[148:151], v[100:103]
	s_waitcnt lgkmcnt(5)
	v_mfma_f32_16x16x32_bf16 v[96:99], v[160:163], v[148:151], v[96:99]
	s_waitcnt lgkmcnt(4)
	v_mfma_f32_16x16x32_bf16 v[92:95], v[210:213], v[148:151], v[92:95]
	s_waitcnt lgkmcnt(3)
	v_mfma_f32_16x16x32_bf16 v[88:91], v[214:217], v[148:151], v[88:91]
	s_waitcnt lgkmcnt(2)
	v_mfma_f32_16x16x32_bf16 v[84:87], v[222:225], v[148:151], v[84:87]
	s_waitcnt lgkmcnt(1)
	v_mfma_f32_16x16x32_bf16 v[0:3], v[0:3], v[148:151], v[112:115]
	s_waitcnt lgkmcnt(0)
	v_mfma_f32_16x16x32_bf16 v[4:7], v[4:7], v[148:151], v[108:111]
	v_add_u32_e32 v16, v202, v204
	v_cvt_pk_bf16_f32 v148, v8, v9
	v_cvt_pk_bf16_f32 v149, v10, v11
	v_cvt_pk_bf16_f32 v150, v12, v13
	v_cvt_pk_bf16_f32 v151, v14, v15
	s_nop 1
	ds_read_b128 v[8:11], v16 offset:49152
	ds_read_b128 v[12:15], v16 offset:51200
	ds_read_b128 v[152:155], v16 offset:53248
	ds_read_b128 v[156:159], v16 offset:55296
	ds_read_b128 v[160:163], v16 offset:57344
	ds_read_b128 v[210:213], v16 offset:59392
	ds_read_b128 v[214:217], v16 offset:61440
	ds_read_b128 v[222:225], v16 offset:63488
	s_waitcnt lgkmcnt(7)
	v_mfma_f32_16x16x32_bf16 v[112:115], v[8:11], v[148:151], v[0:3]
	s_waitcnt lgkmcnt(6)
	v_mfma_f32_16x16x32_bf16 v[108:111], v[12:15], v[148:151], v[4:7]
	s_waitcnt lgkmcnt(5)
	v_mfma_f32_16x16x32_bf16 v[104:107], v[152:155], v[148:151], v[104:107]
	s_waitcnt lgkmcnt(4)
	v_mfma_f32_16x16x32_bf16 v[100:103], v[156:159], v[148:151], v[100:103]
	s_waitcnt lgkmcnt(3)
	v_mfma_f32_16x16x32_bf16 v[96:99], v[160:163], v[148:151], v[96:99]
	s_waitcnt lgkmcnt(2)
	v_mfma_f32_16x16x32_bf16 v[92:95], v[210:213], v[148:151], v[92:95]
	s_waitcnt lgkmcnt(1)
	v_mfma_f32_16x16x32_bf16 v[88:91], v[214:217], v[148:151], v[88:91]
	s_waitcnt lgkmcnt(0)
	v_mfma_f32_16x16x32_bf16 v[84:87], v[222:225], v[148:151], v[84:87]
	v_mov_b32_e32 v176, v209
	v_mov_b32_e32 v18, v208
.Lselb_1642:
	s_or_b64 exec, exec, s[80:81]
	v_and_b32_e32 v0, 0xf0, v207
	v_cmp_ne_u32_e32 vcc, 0, v0
	s_and_saveexec_b64 s[80:81], vcc
	s_cbranch_execz .Lselb_1652
	ds_read_b128 v[0:3], v187 offset:32768
	ds_read_b128 v[4:7], v188 offset:32768
	ds_read_b128 v[8:11], v189 offset:32768
	ds_read_b128 v[12:15], v190 offset:32768
	ds_read_b128 v[148:151], v191 offset:32768
	ds_read_b128 v[152:155], v192 offset:32768
	ds_read_b128 v[156:159], v193 offset:32768
	ds_read_b128 v[208:211], v194 offset:32768
	s_waitcnt lgkmcnt(7)
	v_mfma_f32_16x16x32_bf16 v[0:3], v[0:3], v[36:39], 0
	s_waitcnt lgkmcnt(6)
	v_mfma_f32_16x16x32_bf16 v[4:7], v[4:7], v[36:39], 0
	s_waitcnt lgkmcnt(5)
	v_mfma_f32_16x16x32_bf16 v[0:3], v[8:11], v[40:43], v[0:3]
	s_waitcnt lgkmcnt(4)
	v_mfma_f32_16x16x32_bf16 v[4:7], v[12:15], v[40:43], v[4:7]
	s_waitcnt lgkmcnt(3)
	v_mfma_f32_16x16x32_bf16 v[0:3], v[148:151], v[44:47], v[0:3]
	s_waitcnt lgkmcnt(2)
	v_mfma_f32_16x16x32_bf16 v[4:7], v[152:155], v[44:47], v[4:7]
	s_waitcnt lgkmcnt(1)
	v_mfma_f32_16x16x32_bf16 v[160:163], v[156:159], v[48:51], v[0:3]
	s_waitcnt lgkmcnt(0)
	v_mfma_f32_16x16x32_bf16 v[156:159], v[208:211], v[48:51], v[4:7]
	s_nop 1
	v_lshrrev_b32_e32 v0, 4, v207
	v_and_b32_e32 v0, v0, v186
	v_cmp_ne_u32_e64 s[82:83], 0, v0
	ds_read_b128 v[0:3], v187 offset:40960
	ds_read_b128 v[4:7], v195 offset:32768
	ds_read_b128 v[8:11], v189 offset:40960
	ds_read_b128 v[12:15], v196 offset:32768
	ds_read_b128 v[148:151], v191 offset:40960
	ds_read_b128 v[152:155], v197 offset:32768
	ds_read_b128 v[208:211], v193 offset:40960
	ds_read_b128 v[212:215], v198 offset:32768
	s_waitcnt lgkmcnt(7)
	v_mfma_f32_16x16x32_bf16 v[0:3], v[0:3], v[36:39], 0
	s_waitcnt lgkmcnt(6)
	v_mfma_f32_16x16x32_bf16 v[4:7], v[4:7], v[36:39], 0
	s_waitcnt lgkmcnt(5)
	v_mfma_f32_16x16x32_bf16 v[0:3], v[8:11], v[40:43], v[0:3]
	s_waitcnt lgkmcnt(4)
	v_mfma_f32_16x16x32_bf16 v[4:7], v[12:15], v[40:43], v[4:7]
	s_waitcnt lgkmcnt(3)
	v_mfma_f32_16x16x32_bf16 v[0:3], v[148:151], v[44:47], v[0:3]
	s_waitcnt lgkmcnt(2)
	v_mfma_f32_16x16x32_bf16 v[4:7], v[152:155], v[44:47], v[4:7]
	s_waitcnt lgkmcnt(1)
	v_mfma_f32_16x16x32_bf16 v[152:155], v[208:211], v[48:51], v[0:3]
	s_waitcnt lgkmcnt(0)
	v_mfma_f32_16x16x32_bf16 v[148:151], v[212:215], v[48:51], v[4:7]
	s_lshl_b32 s33, s94, 6
	s_or_b32 s0, s33, 59
	v_cmp_le_i32_e32 vcc, s0, v199
	s_and_saveexec_b64 s[0:1], vcc
	s_xor_b64 s[0:1], exec, s[0:1]
	s_or_saveexec_b64 s[26:27], s[0:1]
	s_mov_b64 s[84:85], s[82:83]
	s_xor_b64 exec, exec, s[26:27]
	s_cbranch_execz .Lselb_1645
	v_cndmask_b32_e64 v1, 0, -1, s[82:83]
	v_or_b32_e32 v2, s33, v201
	v_cndmask_b32_e64 v0, -1, v205, s[82:83]
	v_cmp_gt_i32_e64 s[0:1], v2, v1
	v_or_b32_e32 v1, 2, v2
	v_cmp_le_i32_e64 s[20:21], v1, v0
	v_or_b32_e32 v1, 3, v2
	v_cmp_le_i32_e64 s[22:23], v1, v0
	v_or_b32_e32 v1, 4, v2
	v_cmp_le_i32_e64 s[24:25], v1, v0
	v_or_b32_e32 v1, 5, v2
	v_cmp_le_i32_e64 s[28:29], v1, v0
	v_or_b32_e32 v1, 6, v2
	v_cmp_le_i32_e64 s[30:31], v1, v0
	v_or_b32_e32 v1, 7, v2
	v_cmp_le_i32_e64 s[34:35], v1, v0
	v_or_b32_e32 v1, 32, v2
	v_cmp_le_i32_e64 s[36:37], v1, v0
	v_cmp_lt_i32_e64 s[38:39], v1, v0
	v_or_b32_e32 v1, 34, v2
	v_cmp_le_i32_e64 s[40:41], v1, v0
	v_or_b32_e32 v1, 35, v2
	v_cmp_le_i32_e64 s[42:43], v1, v0
	v_or_b32_e32 v1, 36, v2
	v_cmp_le_i32_e64 s[44:45], v1, v0
	v_or_b32_e32 v1, 37, v2
	v_cmp_le_i32_e64 s[46:47], v1, v0
	v_or_b32_e32 v1, 38, v2
	v_cmp_le_i32_e64 s[18:19], v2, v0
	v_cmp_le_i32_e64 s[48:49], v1, v0
	v_or_b32_e32 v1, 39, v2
	s_and_b64 s[0:1], s[0:1], s[18:19]
	v_cmp_lt_i32_e64 s[18:19], v2, v0
	v_cmp_le_i32_e64 s[50:51], v1, v0
	v_cndmask_b32_e64 v160, v169, v160, s[0:1]
	v_cndmask_b32_e64 v161, v169, v161, s[18:19]
	v_cndmask_b32_e64 v162, v169, v162, s[20:21]
	v_cndmask_b32_e64 v163, v169, v163, s[22:23]
	v_cndmask_b32_e64 v156, v169, v156, s[24:25]
	v_cndmask_b32_e64 v157, v169, v157, s[28:29]
	v_cndmask_b32_e64 v158, v169, v158, s[30:31]
	v_cndmask_b32_e64 v159, v169, v159, s[34:35]
	v_cndmask_b32_e64 v152, v169, v152, s[36:37]
	v_cndmask_b32_e64 v153, v169, v153, s[38:39]
	v_cndmask_b32_e64 v154, v169, v154, s[40:41]
	v_cndmask_b32_e64 v155, v169, v155, s[42:43]
	v_cndmask_b32_e64 v148, v169, v148, s[44:45]
	v_cndmask_b32_e64 v149, v169, v149, s[46:47]
	v_cndmask_b32_e64 v150, v169, v150, s[48:49]
	v_cndmask_b32_e64 v151, v169, v151, s[50:51]
	s_andn2_b64 s[54:55], s[82:83], exec
	s_and_b64 s[50:51], s[50:51], exec
	s_and_b64 s[48:49], s[48:49], exec
	s_and_b64 s[46:47], s[46:47], exec
	s_and_b64 s[44:45], s[44:45], exec
	s_and_b64 s[42:43], s[42:43], exec
	s_and_b64 s[40:41], s[40:41], exec
	s_and_b64 s[38:39], s[38:39], exec
	s_and_b64 s[36:37], s[36:37], exec
	s_and_b64 s[34:35], s[34:35], exec
	s_and_b64 s[30:31], s[30:31], exec
	s_and_b64 s[28:29], s[28:29], exec
	s_and_b64 s[24:25], s[24:25], exec
	s_and_b64 s[22:23], s[22:23], exec
	s_and_b64 s[20:21], s[20:21], exec
	s_and_b64 s[18:19], s[18:19], exec
	s_and_b64 s[0:1], s[0:1], exec
	s_or_b64 s[84:85], s[82:83], exec
	s_or_b64 s[50:51], s[54:55], s[50:51]
	s_or_b64 s[48:49], s[54:55], s[48:49]
	s_or_b64 s[46:47], s[54:55], s[46:47]
	s_or_b64 s[44:45], s[54:55], s[44:45]
	s_or_b64 s[42:43], s[54:55], s[42:43]
	s_or_b64 s[40:41], s[54:55], s[40:41]
	s_or_b64 s[38:39], s[54:55], s[38:39]
	s_or_b64 s[36:37], s[54:55], s[36:37]
	s_or_b64 s[34:35], s[54:55], s[34:35]
	s_or_b64 s[30:31], s[54:55], s[30:31]
	s_or_b64 s[28:29], s[54:55], s[28:29]
	s_or_b64 s[24:25], s[54:55], s[24:25]
	s_or_b64 s[22:23], s[54:55], s[22:23]
	s_or_b64 s[20:21], s[54:55], s[20:21]
	s_or_b64 s[18:19], s[54:55], s[18:19]
	s_or_b64 s[0:1], s[54:55], s[0:1]

.Lselb_1651:
	v_fmac_f32_e32 v208, v175, v16
	v_add_u32_e32 v16, v202, v203
	v_cvt_pk_bf16_f32 v148, v0, v1
	v_cvt_pk_bf16_f32 v149, v2, v3
	v_cvt_pk_bf16_f32 v150, v4, v5
	v_cvt_pk_bf16_f32 v151, v6, v7
	s_nop 1
	ds_read_b128 v[152:155], v16 offset:53248
	ds_read_b128 v[156:159], v16 offset:55296
	ds_read_b128 v[160:163], v16 offset:57344
	ds_read_b128 v[210:213], v16 offset:59392
	ds_read_b128 v[214:217], v16 offset:61440
	ds_read_b128 v[222:225], v16 offset:63488
	ds_read_b128 v[0:3], v16 offset:49152
	ds_read_b128 v[4:7], v16 offset:51200
	s_waitcnt lgkmcnt(7)
	v_mfma_f32_16x16x32_bf16 v[72:75], v[152:155], v[148:151], v[72:75]
	s_waitcnt lgkmcnt(6)
	v_mfma_f32_16x16x32_bf16 v[68:71], v[156:159], v[148:151], v[68:71]
	s_waitcnt lgkmcnt(5)
	v_mfma_f32_16x16x32_bf16 v[64:67], v[160:163], v[148:151], v[64:67]
	s_waitcnt lgkmcnt(4)
	v_mfma_f32_16x16x32_bf16 v[60:63], v[210:213], v[148:151], v[60:63]
	s_waitcnt lgkmcnt(3)
	v_mfma_f32_16x16x32_bf16 v[56:59], v[214:217], v[148:151], v[56:59]
	s_waitcnt lgkmcnt(2)
	v_mfma_f32_16x16x32_bf16 v[52:55], v[222:225], v[148:151], v[52:55]
	s_waitcnt lgkmcnt(1)
	v_mfma_f32_16x16x32_bf16 v[0:3], v[0:3], v[148:151], v[80:83]
	s_waitcnt lgkmcnt(0)
	v_mfma_f32_16x16x32_bf16 v[4:7], v[4:7], v[148:151], v[76:79]
	v_add_u32_e32 v16, v202, v204
	v_cvt_pk_bf16_f32 v148, v8, v9
	v_cvt_pk_bf16_f32 v149, v10, v11
	v_cvt_pk_bf16_f32 v150, v12, v13
	v_cvt_pk_bf16_f32 v151, v14, v15
	s_nop 1
	ds_read_b128 v[8:11], v16 offset:49152
	ds_read_b128 v[12:15], v16 offset:51200
	ds_read_b128 v[152:155], v16 offset:53248
	ds_read_b128 v[156:159], v16 offset:55296
	ds_read_b128 v[160:163], v16 offset:57344
	ds_read_b128 v[210:213], v16 offset:59392
	ds_read_b128 v[214:217], v16 offset:61440
	ds_read_b128 v[222:225], v16 offset:63488
	s_waitcnt lgkmcnt(7)
	v_mfma_f32_16x16x32_bf16 v[80:83], v[8:11], v[148:151], v[0:3]
	s_waitcnt lgkmcnt(6)
	v_mfma_f32_16x16x32_bf16 v[76:79], v[12:15], v[148:151], v[4:7]
	s_waitcnt lgkmcnt(5)
	v_mfma_f32_16x16x32_bf16 v[72:75], v[152:155], v[148:151], v[72:75]
	s_waitcnt lgkmcnt(4)
	v_mfma_f32_16x16x32_bf16 v[68:71], v[156:159], v[148:151], v[68:71]
	s_waitcnt lgkmcnt(3)
	v_mfma_f32_16x16x32_bf16 v[64:67], v[160:163], v[148:151], v[64:67]
	s_waitcnt lgkmcnt(2)
	v_mfma_f32_16x16x32_bf16 v[60:63], v[210:213], v[148:151], v[60:63]
	s_waitcnt lgkmcnt(1)
	v_mfma_f32_16x16x32_bf16 v[56:59], v[214:217], v[148:151], v[56:59]
	s_waitcnt lgkmcnt(0)
	v_mfma_f32_16x16x32_bf16 v[52:55], v[222:225], v[148:151], v[52:55]
	v_mov_b32_e32 v175, v208
	v_mov_b32_e32 v206, v207

.Lsel_exit:
	s_waitcnt vmcnt(0) lgkmcnt(0)
	s_barrier
	s_branch .LBB0_1656
